# adds global write-after-read guards (all 64 team counters past an earlier seam) before phases that overwrite byte ranges aliased by ACT / d_out layouts
# baseline (speedup 1.0000x reference)
; __device__ __forceinline__ unsigned xb_ld(unsigned* p)              { return __hip_atomic_load(p, __ATOMIC_RELAXED, __HIP_MEMORY_SCOPE_AGENT); }
; __device__ __forceinline__ unsigned xb_add(unsigned* p, unsigned v) { return __hip_atomic_fetch_add(p, v, __ATOMIC_RELAXED, __HIP_MEMORY_SCOPE_AGENT); }
; #define XB_SPIN(cond, bar) do { unsigned _sp = 0; while (cond) { __builtin_amdgcn_s_sleep(1); \
;     if ((++_sp & 255u) == 0u) { if (xb_ld(&(bar)[XB_TMO])) break; if (_sp > XB_SPIN_CAP) { atomicAdd(&(bar)[XB_TMO], 1u); break; } } } } while (0)
; __device__ __forceinline__ void xcd_barrier(const XcdBarrier& b) {
;     ...
;             else XB_SPIN(xb_ld(&bar[XB_TOPGEN]) == tg, bar);
;             __builtin_amdgcn_fence(__ATOMIC_ACQUIRE, "agent");
;             xb_add(&bar[XB_XGEN(b.x)], 1u);
;             asm volatile("s_waitcnt vmcnt(0)" ::: "memory");
;         } else {
;             XB_SPIN(xb_ld(&bar[XB_XGEN(b.x)]) == gen, bar);
;             __builtin_amdgcn_fence(__ATOMIC_ACQUIRE, "agent");
;             asm volatile("s_waitcnt vmcnt(0)" ::: "memory");
;         }
.Ltb482_srel:
	s_mov_b64 exec, -1
	v_lshlrev_b32_e32 v4, 5, v195
.Ltb482_sgs:
	global_load_dword v5, v4, s[8:9] sc1
	s_waitcnt vmcnt(0)
	v_cmp_gt_u32_e32 vcc, 8, v5
	s_cmp_lg_u64 vcc, 0
	s_cbranch_scc0 .Ltb482_sgd
	s_sleep 1
	s_add_u32 s15, s15, 1
	s_cmp_lt_u32 s15, 0x400000
	s_cbranch_scc1 .Ltb482_sgs
.Ltb482_sgd:
	s_mov_b64 exec, 1
	buffer_inv sc1
	s_waitcnt vmcnt(0)
	s_branch .Ltb482_done

; __device__ __forceinline__ void xcd_barrier(const XcdBarrier& b) {
;     ...
;             __builtin_amdgcn_fence(__ATOMIC_ACQUIRE, "agent");
;             asm volatile("s_waitcnt vmcnt(0)" ::: "memory");
;         }
;     }
;     __syncthreads();
.Ltb482_fgd:
	s_mov_b64 exec, 1

; __device__ __forceinline__ unsigned xb_ld(unsigned* p)              { return __hip_atomic_load(p, __ATOMIC_RELAXED, __HIP_MEMORY_SCOPE_AGENT); }
; __device__ __forceinline__ unsigned xb_add(unsigned* p, unsigned v) { return __hip_atomic_fetch_add(p, v, __ATOMIC_RELAXED, __HIP_MEMORY_SCOPE_AGENT); }
; #define XB_SPIN(cond, bar) do { unsigned _sp = 0; while (cond) { __builtin_amdgcn_s_sleep(1); \
;     if ((++_sp & 255u) == 0u) { if (xb_ld(&(bar)[XB_TMO])) break; if (_sp > XB_SPIN_CAP) { atomicAdd(&(bar)[XB_TMO], 1u); break; } } } } while (0)
; __device__ __forceinline__ void xcd_barrier(const XcdBarrier& b) {
;     ...
;             else XB_SPIN(xb_ld(&bar[XB_TOPGEN]) == tg, bar);
;             __builtin_amdgcn_fence(__ATOMIC_ACQUIRE, "agent");
;             xb_add(&bar[XB_XGEN(b.x)], 1u);
;             asm volatile("s_waitcnt vmcnt(0)" ::: "memory");
;         } else {
;             XB_SPIN(xb_ld(&bar[XB_XGEN(b.x)]) == gen, bar);
.Ltb1039_sgs:
	global_load_dword v5, v4, s[8:9] sc1
	s_waitcnt vmcnt(0)
	v_cmp_gt_u32_e32 vcc, 28, v5
	s_cmp_lg_u64 vcc, 0
	s_cbranch_scc0 .Ltb1039_sgd
	s_sleep 1
	s_add_u32 s15, s15, 1
	s_cmp_lt_u32 s15, 0x400000
	s_cbranch_scc1 .Ltb1039_sgs

; __device__ __forceinline__ unsigned xb_ld(unsigned* p)              { return __hip_atomic_load(p, __ATOMIC_RELAXED, __HIP_MEMORY_SCOPE_AGENT); }
; __device__ __forceinline__ unsigned xb_add(unsigned* p, unsigned v) { return __hip_atomic_fetch_add(p, v, __ATOMIC_RELAXED, __HIP_MEMORY_SCOPE_AGENT); }
; #define XB_SPIN(cond, bar) do { unsigned _sp = 0; while (cond) { __builtin_amdgcn_s_sleep(1); \
;     if ((++_sp & 255u) == 0u) { if (xb_ld(&(bar)[XB_TMO])) break; if (_sp > XB_SPIN_CAP) { atomicAdd(&(bar)[XB_TMO], 1u); break; } } } } while (0)
; __device__ __forceinline__ void xcd_barrier(const XcdBarrier& b) {
;     ...
;             else XB_SPIN(xb_ld(&bar[XB_TOPGEN]) == tg, bar);
;             __builtin_amdgcn_fence(__ATOMIC_ACQUIRE, "agent");
;             xb_add(&bar[XB_XGEN(b.x)], 1u);
;             asm volatile("s_waitcnt vmcnt(0)" ::: "memory");
;         } else {
;             XB_SPIN(xb_ld(&bar[XB_XGEN(b.x)]) == gen, bar);
.Ltb1309_sgs:
	global_load_dword v5, v4, s[8:9] sc1
	s_waitcnt vmcnt(0)
	v_cmp_gt_u32_e32 vcc, 40, v5
	s_cmp_lg_u64 vcc, 0
	s_cbranch_scc0 .Ltb1309_sgd
	s_sleep 1
	s_add_u32 s15, s15, 1
	s_cmp_lt_u32 s15, 0x400000
	s_cbranch_scc1 .Ltb1309_sgs
